# static priority raise of the late wave half in both GEMM main loops set to level 3 instead of 1
# speedup vs baseline: 1.0010x; 1.0010x over previous
.LBB0_201:
	s_cmp_eq_u32 s0, 1
	s_cbranch_scc0 .Lg1_noprio
	s_setprio 3
